# GEMM5 epilogue: the 8 serialized row-statistics load rounds (2 loads, wait, repeat) issued ahead instead of one exposed round trip each
# speedup vs baseline: 1.0039x; 1.0029x over previous
; #define GAS __attribute__((address_space(1)))
;     __device__ __forceinline__ void operator()(const f32x4 (&acc)[2][2][4][2], const pg8::Unit& u, int wr, int wc, int fr, int fq) const {
;     ...
;         for (int i = 0; i < 8; ++i) { const int row = row0 + (i >> 2) * 128 + (i & 3) * 16;
;             const f32x4 p0 = *(const GAS f32x4*)(ssq + (size_t)row * 32 + fq * 8), p1 = *(const GAS f32x4*)(ssq + (size_t)row * 32 + fq * 8 + 4);
;             rs[i] = (p0[0] + p0[1]) + (p0[2] + p0[3]) + (p1[0] + p1[1]) + (p1[2] + p1[3]); }
.LBB0_663:
	v_lshl_add_u32 v200, s9, 8, v179
	v_ashrrev_i32_e32 v201, 31, v200
	v_lshlrev_b64 v[36:37], 7, v[200:201]
	v_lshl_add_u64 v[40:41], v[194:195], 0, v[36:37]
	global_load_dwordx4 v[36:39], v[40:41], off offset:16
	s_nop 0
	global_load_dwordx4 v[40:43], v[40:41], off
	s_nop 1
	v_or_b32_e32 v251, 16, v200
	v_ashrrev_i32_e32 v250, 31, v251
	v_mov_b32_e32 v234, v251
	v_mov_b32_e32 v235, v250
	v_lshlrev_b64 v[236:237], 7, v[234:235]
	v_lshl_add_u64 v[232:233], v[194:195], 0, v[236:237]
	global_load_dwordx4 v[228:231], v[232:233], off offset:16
	v_or_b32_e32 v251, 16, v200
	v_ashrrev_i32_e32 v250, 31, v251
	v_mov_b32_e32 v234, v251
	v_mov_b32_e32 v235, v250
	v_lshlrev_b64 v[236:237], 7, v[234:235]
	v_lshl_add_u64 v[232:233], v[194:195], 0, v[236:237]
	global_load_dwordx4 v[224:227], v[232:233], off
	v_or_b32_e32 v251, 32, v200
	v_ashrrev_i32_e32 v250, 31, v251
	v_mov_b32_e32 v234, v251
	v_mov_b32_e32 v235, v250
	v_lshlrev_b64 v[236:237], 7, v[234:235]
	v_lshl_add_u64 v[232:233], v[194:195], 0, v[236:237]
	global_load_dwordx4 v[214:217], v[232:233], off offset:16
	v_or_b32_e32 v251, 32, v200
	v_ashrrev_i32_e32 v250, 31, v251
	v_mov_b32_e32 v234, v251
	v_mov_b32_e32 v235, v250
	v_lshlrev_b64 v[236:237], 7, v[234:235]
	v_lshl_add_u64 v[232:233], v[194:195], 0, v[236:237]
	global_load_dwordx4 v[96:99], v[232:233], off
	v_or_b32_e32 v251, 48, v200
	v_ashrrev_i32_e32 v250, 31, v251
	v_mov_b32_e32 v234, v251
	v_mov_b32_e32 v235, v250
	v_lshlrev_b64 v[236:237], 7, v[234:235]
	v_lshl_add_u64 v[232:233], v[194:195], 0, v[236:237]
	global_load_dwordx4 v[84:87], v[232:233], off offset:16
	v_or_b32_e32 v251, 48, v200
	v_ashrrev_i32_e32 v250, 31, v251
	v_mov_b32_e32 v234, v251
	v_mov_b32_e32 v235, v250
	v_lshlrev_b64 v[236:237], 7, v[234:235]
	v_lshl_add_u64 v[232:233], v[194:195], 0, v[236:237]
	global_load_dwordx4 v[80:83], v[232:233], off
	v_add_u32_e32 v251, 0x80, v200
	v_ashrrev_i32_e32 v250, 31, v251
	v_mov_b32_e32 v234, v251
	v_mov_b32_e32 v235, v250
	v_lshlrev_b64 v[236:237], 7, v[234:235]
	v_lshl_add_u64 v[232:233], v[194:195], 0, v[236:237]
	global_load_dwordx4 v[76:79], v[232:233], off offset:16
	v_add_u32_e32 v251, 0x80, v200
	v_ashrrev_i32_e32 v250, 31, v251
	v_mov_b32_e32 v234, v251
	v_mov_b32_e32 v235, v250
	v_lshlrev_b64 v[236:237], 7, v[234:235]
	v_lshl_add_u64 v[232:233], v[194:195], 0, v[236:237]
	global_load_dwordx4 v[48:51], v[232:233], off
	v_or_b32_e32 v218, 16, v200
	v_ashrrev_i32_e32 v219, 31, v218
	v_or_b32_e32 v210, 32, v200
	v_ashrrev_i32_e32 v211, 31, v210
	v_or_b32_e32 v208, 48, v200
	v_ashrrev_i32_e32 v209, 31, v208
	v_add_u32_e32 v206, 0x80, v200
	v_ashrrev_i32_e32 v207, 31, v206
	v_lshl_or_b32 v212, s22, 7, v244
	v_ashrrev_i32_e32 v213, 31, v212
	v_readlane_b32 s88, v252, 0
	v_readlane_b32 s90, v252, 2
	v_readlane_b32 s91, v252, 3
	s_mov_b64 s[0:1], 0x5600
	v_readlane_b32 s92, v252, 4
	v_readlane_b32 s93, v252, 5
	v_xor_b32_e32 v201, 16, v173
	s_mov_b32 s16, 0x3a000000
	v_readlane_b32 s89, v252, 1
	v_readlane_b32 s94, v252, 6
	v_readlane_b32 s95, v252, 7
	s_waitcnt vmcnt(8)
	v_mov_b32_e32 v44, v41
	v_mov_b32_e32 v45, v42
	v_mov_b32_e32 v41, v43
	v_pk_add_f32 v[166:167], v[44:45], v[40:41]
	v_mov_b32_e32 v40, v38
	v_mov_b32_e32 v41, v36
	v_mov_b32_e32 v36, v39
	v_pk_add_f32 v[164:165], v[40:41], v[36:37]
	v_lshlrev_b64 v[36:37], 7, v[218:219]
	v_lshl_add_u64 v[40:41], v[194:195], 0, v[36:37]
	s_nop 0
	s_nop 0
	s_nop 0
	v_mov_b32_e32 v233, v166
	s_waitcnt vmcnt(6)
	v_mov_b32_e32 v44, v225
	v_mov_b32_e32 v45, v226
	v_mov_b32_e32 v41, v227
	v_mov_b32_e32 v222, v224
	v_mov_b32_e32 v223, v41
	v_pk_add_f32 v[170:171], v[44:45], v[222:223]
	v_mov_b32_e32 v40, v230
	v_mov_b32_e32 v41, v228
	v_mov_b32_e32 v36, v231
	v_mov_b32_e32 v226, v36
	v_mov_b32_e32 v227, v229
	v_pk_add_f32 v[168:169], v[40:41], v[226:227]
	v_lshlrev_b64 v[36:37], 7, v[210:211]
	v_lshl_add_u64 v[40:41], v[194:195], 0, v[36:37]
	s_nop 0
	s_nop 0
	s_nop 0
	v_mov_b32_e32 v232, v170
	v_mov_b32_e32 v166, v171
	v_pk_add_f32 v[166:167], v[232:233], v[166:167]
	v_mov_b32_e32 v170, v169
	v_mov_b32_e32 v171, v165
	v_pk_add_f32 v[166:167], v[166:167], v[170:171]
	v_mov_b32_e32 v169, v164
	v_pk_add_f32 v[164:165], v[168:169], v[166:167]
	s_waitcnt vmcnt(4)
	v_mov_b32_e32 v44, v97
	v_mov_b32_e32 v45, v98
	v_mov_b32_e32 v41, v99
	v_mov_b32_e32 v230, v96
	v_mov_b32_e32 v231, v41
	v_pk_add_f32 v[204:205], v[44:45], v[230:231]
	v_mov_b32_e32 v40, v216
	v_mov_b32_e32 v41, v214
	v_mov_b32_e32 v36, v217
	v_mov_b32_e32 v230, v36
	v_mov_b32_e32 v231, v215
	v_pk_add_f32 v[202:203], v[40:41], v[230:231]
	v_lshlrev_b64 v[36:37], 7, v[208:209]
	v_lshl_add_u64 v[40:41], v[194:195], 0, v[36:37]
	s_nop 0
	s_nop 0
	s_nop 0
	v_xor_b32_e32 v209, 32, v173
	s_waitcnt vmcnt(2)
	v_add_u32_e32 v251, 0x90, v200
	v_ashrrev_i32_e32 v250, 31, v251
	v_mov_b32_e32 v234, v251
	v_mov_b32_e32 v235, v250
	v_lshlrev_b64 v[236:237], 7, v[234:235]
	v_lshl_add_u64 v[232:233], v[194:195], 0, v[236:237]
	global_load_dwordx4 v[96:99], v[232:233], off offset:16
	v_mov_b32_e32 v44, v81
	v_mov_b32_e32 v45, v82
	v_mov_b32_e32 v41, v83
	v_mov_b32_e32 v230, v80
	v_mov_b32_e32 v231, v41
	v_pk_add_f32 v[222:223], v[44:45], v[230:231]
	v_mov_b32_e32 v40, v86
	v_mov_b32_e32 v41, v84
	v_mov_b32_e32 v36, v87
	v_mov_b32_e32 v230, v36
	v_mov_b32_e32 v231, v85
	v_pk_add_f32 v[220:221], v[40:41], v[230:231]
	v_lshlrev_b64 v[36:37], 7, v[206:207]
	v_lshl_add_u64 v[40:41], v[194:195], 0, v[36:37]
	s_nop 0
	s_nop 0
	s_nop 0
	v_and_b32_e32 v207, 64, v173
	v_add_u32_e32 v207, 64, v207
	s_waitcnt vmcnt(1)
; #define GAS __attribute__((address_space(1)))
;     __device__ __forceinline__ void operator()(const f32x4 (&acc)[2][2][4][2], const pg8::Unit& u, int wr, int wc, int fr, int fq) const {
;     ...
;         for (int i = 0; i < 8; ++i) { const int row = row0 + (i >> 2) * 128 + (i & 3) * 16;
;             const f32x4 p0 = *(const GAS f32x4*)(ssq + (size_t)row * 32 + fq * 8), p1 = *(const GAS f32x4*)(ssq + (size_t)row * 32 + fq * 8 + 4);
;             rs[i] = (p0[0] + p0[1]) + (p0[2] + p0[3]) + (p1[0] + p1[1]) + (p1[2] + p1[3]); }
;         float w0[8], w1[8], w2[8], bb[8];
; #pragma unroll
;         for (int e = 0; e < 8; ++e) { w0[e] = cw[0 * DFF + ch0 + e]; w1[e] = cw[1 * DFF + ch0 + e]; w2[e] = cw[2 * DFF + ch0 + e]; bb[e] = cb[ch0 + e]; }
; #pragma unroll
;         for (int i = 0; i < 8; ++i) { float s = rs[i]; s += __shfl_xor(s, 16); s += __shfl_xor(s, 32); rs[i] = rsqrtf(s * (1.f / DM) + EPS); }
	v_add_u32_e32 v251, 0x90, v200
	v_ashrrev_i32_e32 v250, 31, v251
	v_mov_b32_e32 v234, v251
	v_mov_b32_e32 v235, v250
	v_lshlrev_b64 v[236:237], 7, v[234:235]
	v_lshl_add_u64 v[232:233], v[194:195], 0, v[236:237]
	global_load_dwordx4 v[84:87], v[232:233], off
	v_add_u32_e32 v251, 0xa0, v200
	v_ashrrev_i32_e32 v250, 31, v251
	v_mov_b32_e32 v234, v251
	v_mov_b32_e32 v235, v250
	v_lshlrev_b64 v[236:237], 7, v[234:235]
	v_lshl_add_u64 v[232:233], v[194:195], 0, v[236:237]
	global_load_dwordx4 v[80:83], v[232:233], off offset:16
	v_mov_b32_e32 v44, v49
	v_mov_b32_e32 v45, v50
	v_mov_b32_e32 v41, v51
	v_mov_b32_e32 v230, v48
	v_mov_b32_e32 v231, v41
	v_pk_add_f32 v[216:217], v[44:45], v[230:231]
	v_mov_b32_e32 v40, v78
	v_mov_b32_e32 v41, v76
	v_mov_b32_e32 v36, v79
	v_mov_b32_e32 v230, v36
	v_mov_b32_e32 v231, v77
	v_pk_add_f32 v[214:215], v[40:41], v[230:231]
	v_add_u32_e32 v36, 0x90, v200
	v_ashrrev_i32_e32 v37, 31, v36
	v_lshlrev_b64 v[36:37], 7, v[36:37]
	v_lshl_add_u64 v[40:41], v[194:195], 0, v[36:37]
	s_nop 0
	s_nop 0
	s_nop 0
	v_mov_b32_e32 v169, v215
	s_waitcnt vmcnt(1)
	v_add_u32_e32 v251, 0xa0, v200
	v_ashrrev_i32_e32 v250, 31, v251
	v_mov_b32_e32 v234, v251
	v_mov_b32_e32 v235, v250
	v_lshlrev_b64 v[236:237], 7, v[234:235]
	v_lshl_add_u64 v[232:233], v[194:195], 0, v[236:237]
	global_load_dwordx4 v[76:79], v[232:233], off
	v_add_u32_e32 v251, 0xb0, v200
	v_ashrrev_i32_e32 v250, 31, v251
	v_mov_b32_e32 v234, v251
	v_mov_b32_e32 v235, v250
	v_lshlrev_b64 v[236:237], 7, v[234:235]
	v_lshl_add_u64 v[232:233], v[194:195], 0, v[236:237]
	global_load_dwordx4 v[48:51], v[232:233], off offset:16
	v_mov_b32_e32 v44, v85
	v_mov_b32_e32 v45, v86
	v_mov_b32_e32 v41, v87
	v_mov_b32_e32 v230, v84
	v_mov_b32_e32 v231, v41
	v_pk_add_f32 v[226:227], v[44:45], v[230:231]
	v_mov_b32_e32 v40, v98
	v_mov_b32_e32 v41, v96
	v_mov_b32_e32 v36, v99
	v_mov_b32_e32 v230, v36
	v_mov_b32_e32 v231, v97
	v_pk_add_f32 v[224:225], v[40:41], v[230:231]
	v_add_u32_e32 v36, 0xa0, v200
	v_ashrrev_i32_e32 v37, 31, v36
	v_lshlrev_b64 v[36:37], 7, v[36:37]
	v_lshl_add_u64 v[40:41], v[194:195], 0, v[36:37]
	s_nop 0
	s_nop 0
	s_nop 0
	v_mov_b32_e32 v168, v225
	v_mov_b32_e32 v225, v214
	s_waitcnt vmcnt(1)
	v_add_u32_e32 v251, 0xb0, v200
	v_ashrrev_i32_e32 v250, 31, v251
	v_mov_b32_e32 v234, v251
	v_mov_b32_e32 v235, v250
	v_lshlrev_b64 v[236:237], 7, v[234:235]
	v_lshl_add_u64 v[232:233], v[194:195], 0, v[236:237]
	global_load_dwordx4 v[96:99], v[232:233], off
	v_mov_b32_e32 v44, v77
	v_mov_b32_e32 v45, v78
	v_mov_b32_e32 v41, v79
	v_mov_b32_e32 v228, v76
	v_mov_b32_e32 v229, v41
	v_pk_add_f32 v[230:231], v[44:45], v[228:229]
	v_mov_b32_e32 v40, v82
	v_mov_b32_e32 v41, v80
	v_mov_b32_e32 v36, v83
	v_mov_b32_e32 v214, v36
	v_mov_b32_e32 v215, v81
	v_pk_add_f32 v[228:229], v[40:41], v[214:215]
	v_add_u32_e32 v36, 0xb0, v200
	v_ashrrev_i32_e32 v37, 31, v36
	v_lshlrev_b64 v[36:37], 7, v[36:37]
	v_lshl_add_u64 v[40:41], v[194:195], 0, v[36:37]
	s_nop 0
	s_nop 0
	s_nop 0
	s_waitcnt vmcnt(0)
	v_mov_b32_e32 v44, v97
	v_mov_b32_e32 v45, v98
	v_mov_b32_e32 v41, v99
	v_mov_b32_e32 v214, v96
	v_mov_b32_e32 v215, v41
	v_pk_add_f32 v[250:251], v[44:45], v[214:215]
	v_lshlrev_b64 v[44:45], 2, v[212:213]
	v_lshl_add_u64 v[46:47], s[90:91], 0, v[44:45]
	v_mov_b32_e32 v40, v50
	v_mov_b32_e32 v41, v48
	v_mov_b32_e32 v36, v51
	v_add_co_u32_e32 v42, vcc, s5, v46
	v_mov_b32_e32 v214, v36
	v_mov_b32_e32 v215, v49
	v_pk_add_f32 v[236:237], v[40:41], v[214:215]
	v_lshl_add_u64 v[40:41], v[46:47], 0, s[0:1]
	v_addc_co_u32_e32 v43, vcc, 0, v47, vcc
	s_mov_b64 s[0:1], 0xac00
	global_load_dwordx4 v[36:39], v[46:47], off offset:16
	global_load_dwordx4 v[76:79], v[46:47], off
	v_lshl_add_u64 v[48:49], v[46:47], 0, s[0:1]
	v_add_co_u32_e32 v46, vcc, s4, v46
	v_lshl_add_u64 v[84:85], s[92:93], 0, v[44:45]
	s_nop 0
	v_addc_co_u32_e32 v47, vcc, 0, v47, vcc
	global_load_dwordx4 v[80:83], v[42:43], off offset:1536
	s_nop 0
	global_load_dwordx4 v[40:43], v[40:41], off offset:16
	s_nop 0
	global_load_dwordx4 v[96:99], v[46:47], off offset:3072
	s_nop 0
	global_load_dwordx4 v[48:51], v[48:49], off offset:16
	s_nop 0
	global_load_dwordx4 v[44:47], v[84:85], off offset:16
	s_nop 0
	global_load_dwordx4 v[84:87], v[84:85], off
	v_cmp_lt_i32_e32 vcc, v201, v207
	s_mov_b32 s0, 0x358637bd
	s_nop 0
	v_cndmask_b32_e32 v201, v173, v201, vcc
	v_lshlrev_b32_e32 v201, 2, v201
	ds_bpermute_b32 v167, v201, v165
	ds_bpermute_b32 v166, v201, v164
	v_cmp_lt_i32_e32 vcc, v209, v207
	s_waitcnt lgkmcnt(0)
; #define LAS __attribute__((address_space(3)))
;     __device__ __forceinline__ void operator()(const f32x4 (&acc)[2][2][4][2], const pg8::Unit& u, int wr, int wc, int fr, int fq) const {
;     ...
;         for (int i = 0; i < 8; ++i) { float s = rs[i]; s += __shfl_xor(s, 16); s += __shfl_xor(s, 32); rs[i] = rsqrtf(s * (1.f / DM) + EPS); }
;         float us[2][4][8];
; #pragma unroll
;         for (int ai = 0; ai < 2; ++ai)
; #pragma unroll
;             for (int m = 0; m < 4; ++m) { const float r = rs[ai * 4 + m];
; #pragma unroll
;                 for (int e = 0; e < 4; ++e) { us[ai][m][e] = acc[ai][0][m][0][e] * r; us[ai][m][4 + e] = acc[ai][0][m][1][e] * r; } }
;         if (fr >= 14) {
; #pragma unroll
;             for (int ai = 0; ai < 2; ++ai) { LAS float* xp = xch + ((2 * ai + wr) * 2 + (fr - 14)) * 128 + lc;
;                 *(LAS f32x4*)xp = (f32x4){us[ai][3][0], us[ai][3][1], us[ai][3][2], us[ai][3][3]}; *(LAS f32x4*)(xp + 4) = (f32x4){us[ai][3][4], us[ai][3][5], us[ai][3][6], us[ai][3][7]}; } }
	v_pk_add_f32 v[232:233], v[164:165], v[166:167]
	v_mov_b32_e32 v164, v222
	v_mov_b32_e32 v165, v204
	v_mov_b32_e32 v204, v223
	v_pk_add_f32 v[164:165], v[164:165], v[204:205]
	v_mov_b32_e32 v166, v221
	v_mov_b32_e32 v167, v203
	v_pk_add_f32 v[164:165], v[164:165], v[166:167]
	v_mov_b32_e32 v221, v202
	v_pk_add_f32 v[164:165], v[220:221], v[164:165]
	ds_bpermute_b32 v167, v201, v165
	ds_bpermute_b32 v166, v201, v164
	v_cndmask_b32_e32 v207, v173, v209, vcc
	v_lshlrev_b32_e32 v207, 2, v207
	ds_bpermute_b32 v235, v207, v233
	ds_bpermute_b32 v234, v207, v232
	s_waitcnt lgkmcnt(2)
	v_pk_add_f32 v[164:165], v[164:165], v[166:167]
	ds_bpermute_b32 v167, v207, v165
	ds_bpermute_b32 v166, v207, v164
	s_waitcnt lgkmcnt(0)
	v_pk_add_f32 v[164:165], v[164:165], v[166:167]
	v_mov_b64_e32 v[166:167], s[0:1]
	v_pk_fma_f32 v[220:221], v[164:165], s[16:17], v[166:167] op_sel_hi:[1,0,0]
	s_nop 0
	v_cmp_gt_f32_e32 vcc, s7, v220
	v_mul_f32_e32 v164, 0x4b800000, v220
	v_cmp_gt_f32_e64 s[44:45], s7, v221
	v_cndmask_b32_e32 v164, v220, v164, vcc
	v_rsq_f32_e32 v164, v164
	s_nop 0
	v_mul_f32_e32 v165, 0x45800000, v164
	v_cndmask_b32_e32 v220, v164, v165, vcc
	v_mov_b32_e32 v164, v226
	v_mov_b32_e32 v165, v216
	v_mov_b32_e32 v216, v227
	v_pk_add_f32 v[164:165], v[164:165], v[216:217]
	v_pk_mul_f32 v[160:161], v[160:161], v[220:221] op_sel_hi:[1,0]
	v_pk_add_f32 v[164:165], v[164:165], v[168:169]
	v_pk_mul_f32 v[156:157], v[156:157], v[220:221] op_sel_hi:[1,0]
	v_pk_add_f32 v[164:165], v[224:225], v[164:165]
	ds_bpermute_b32 v169, v201, v165
	ds_bpermute_b32 v168, v201, v164
	v_pk_mul_f32 v[162:163], v[162:163], v[220:221] op_sel_hi:[1,0]
	v_pk_mul_f32 v[158:159], v[158:159], v[220:221] op_sel_hi:[1,0]
	s_waitcnt lgkmcnt(0)
	v_pk_add_f32 v[214:215], v[164:165], v[168:169]
	v_mov_b32_e32 v164, v250
	v_mov_b32_e32 v165, v230
	v_mov_b32_e32 v230, v251
	v_pk_add_f32 v[164:165], v[164:165], v[230:231]
	v_mov_b32_e32 v168, v237
	v_mov_b32_e32 v169, v229
	v_pk_add_f32 v[164:165], v[164:165], v[168:169]
	v_mov_b32_e32 v237, v228
	v_pk_add_f32 v[164:165], v[236:237], v[164:165]
	ds_bpermute_b32 v169, v201, v165
	ds_bpermute_b32 v168, v201, v164
	ds_bpermute_b32 v217, v207, v215
	ds_bpermute_b32 v216, v207, v214
	s_waitcnt lgkmcnt(2)
	v_pk_add_f32 v[164:165], v[164:165], v[168:169]
	ds_bpermute_b32 v169, v207, v165
	ds_bpermute_b32 v168, v207, v164
	s_waitcnt lgkmcnt(0)
	v_pk_add_f32 v[164:165], v[164:165], v[168:169]
	s_nop 0
	v_pk_fma_f32 v[202:203], v[164:165], s[16:17], v[166:167] op_sel_hi:[1,0,0]
	s_nop 0
	v_cmp_gt_f32_e32 vcc, s7, v202
	v_mul_f32_e32 v164, 0x4b800000, v202
	v_cmp_gt_f32_e64 s[42:43], s7, v203
	v_cndmask_b32_e32 v164, v202, v164, vcc
	v_rsq_f32_e32 v164, v164
	s_nop 0
	v_mul_f32_e32 v165, 0x45800000, v164
	v_cndmask_b32_e32 v202, v164, v165, vcc
	v_pk_mul_f32 v[92:93], v[92:93], v[202:203] op_sel_hi:[1,0]
	v_pk_mul_f32 v[88:89], v[88:89], v[202:203] op_sel_hi:[1,0]
	v_pk_mul_f32 v[94:95], v[94:95], v[202:203] op_sel_hi:[1,0]
	v_pk_mul_f32 v[90:91], v[90:91], v[202:203] op_sel_hi:[1,0]
	s_and_saveexec_b64 s[0:1], s[36:37]
	s_cbranch_execz .LBB0_665
	ds_write_b128 v246, v[160:163]
	ds_write_b128 v246, v[156:159] offset:16
	ds_write_b128 v245, v[92:95]
	ds_write_b128 v245, v[88:91] offset:16
